# gate/up GEMM phases: closed-form next-unit schedule (magic-multiply division) replaces the generic 92-instruction S.next arithmetic
# speedup vs baseline: 1.0106x; 1.0049x over previous
.LBB0_167:
	s_add_i32 s85, s85, 1
	s_mul_i32 s7, s85, s42
	s_add_i32 s7, s7, s2
	s_cmpk_lt_i32 s7, 0xbb0
	s_cselect_b64 s[48:49], -1, 0
	s_cmpk_gt_i32 s7, 0xbaf
	s_cbranch_scc1 .LBB0_169
	v_mov_b32_e32 v8, s75
	v_mov_b32_e32 v7, s74
	ds_read_b32 v162, v7
	ds_read_b128 v[6:9], v8
	s_and_b32 s58, s7, 7
	s_lshr_b32 s51, s7, 3
	s_mul_i32 s58, s58, 0x176
	s_add_i32 s58, s58, s51
	s_mul_i32 s51, s58, 0xba3
	s_lshr_b32 s51, s51, 19
	s_mul_i32 s55, s51, 0xb0
	s_sub_i32 s58, s58, s55
	s_and_b32 s55, s58, 7
	s_lshl_b32 s51, s51, 3
	s_add_i32 s54, s51, s55
	s_lshr_b32 s50, s58, 3
	s_lshl_b32 s58, s54, 19
	s_mov_b32 s59, 0
	s_waitcnt lgkmcnt(0)
	v_lshl_add_u64 v[146:147], v[6:7], 0, s[58:59]
	s_lshl_b32 s58, s50, 19
	v_lshl_add_u64 v[148:149], v[8:9], 0, s[58:59]

.LBB0_945:
	s_add_i32 s83, s83, 1
	s_mul_i32 s7, s83, s42
	s_add_i32 s7, s7, s2
	s_cmpk_lt_i32 s7, 0xb00
	s_cselect_b64 s[44:45], -1, 0
	s_cmpk_gt_i32 s7, 0xaff
	s_cbranch_scc1 .LBB0_947
	v_mov_b32_e32 v8, s73
	v_mov_b32_e32 v7, s72
	ds_read_b32 v162, v7
	ds_read_b128 v[6:9], v8
	s_and_b32 s56, s7, 7
	s_lshr_b32 s47, s7, 3
	s_mul_i32 s56, s56, 0x160
	s_add_i32 s56, s56, s47
	s_mul_i32 s47, s56, 0xba3
	s_lshr_b32 s47, s47, 19
	s_mul_i32 s49, s47, 0xb0
	s_sub_i32 s56, s56, s49
	s_and_b32 s49, s56, 7
	s_lshl_b32 s47, s47, 3
	s_add_i32 s48, s47, s49
	s_lshr_b32 s46, s56, 3
	s_lshl_b32 s56, s48, 19
	s_mov_b32 s57, 0
	s_waitcnt lgkmcnt(0)
	v_lshl_add_u64 v[146:147], v[6:7], 0, s[56:57]
	s_lshl_b32 s56, s46, 19
	v_lshl_add_u64 v[148:149], v[8:9], 0, s[56:57]

.LBB0_1940:
	s_add_i32 s81, s81, 1
	s_mul_i32 s5, s81, s42
	s_add_i32 s5, s5, s2
	s_cmpk_lt_i32 s5, 0xb00
	s_cselect_b64 s[28:29], -1, 0
	s_cmpk_gt_i32 s5, 0xaff
	s_cbranch_scc1 .LBB0_1942
	v_mov_b32_e32 v8, s71
	v_mov_b32_e32 v7, s70
	ds_read_b32 v162, v7
	ds_read_b128 v[6:9], v8
	s_and_b32 s50, s5, 7
	s_lshr_b32 s45, s5, 3
	s_mul_i32 s50, s50, 0x160
	s_add_i32 s50, s50, s45
	s_mul_i32 s45, s50, 0xba3
	s_lshr_b32 s45, s45, 19
	s_mul_i32 s47, s45, 0xb0
	s_sub_i32 s50, s50, s47
	s_and_b32 s47, s50, 7
	s_lshl_b32 s45, s45, 3
	s_add_i32 s46, s45, s47
	s_lshr_b32 s44, s50, 3
	s_lshl_b32 s50, s46, 19
	s_mov_b32 s51, 0
	s_waitcnt lgkmcnt(0)
	v_lshl_add_u64 v[146:147], v[6:7], 0, s[50:51]
	s_lshl_b32 s50, s44, 19
	v_lshl_add_u64 v[148:149], v[8:9], 0, s[50:51]
